# speedup vs baseline: 1.0131x; 1.0118x over previous
;     ...
;   {
;     int k = t >> 3, n0 = (t & 7) * 8;
;     const float4* s = (const float4*)(src + (size_t)(kt * 64 + k) * N + ntile * 64 + n0);
;     float4 a = s[0], b = s[1];
;     tl[(n0 + 0) * 66 + k] = f2bf(a.x); tl[(n0 + 1) * 66 + k] = f2bf(a.y);
;     tl[(n0 + 2) * 66 + k] = f2bf(a.z); tl[(n0 + 3) * 66 + k] = f2bf(a.w);
;     tl[(n0 + 4) * 66 + k] = f2bf(b.x); tl[(n0 + 5) * 66 + k] = f2bf(b.y);
;     tl[(n0 + 6) * 66 + k] = f2bf(b.z); tl[(n0 + 7) * 66 + k] = f2bf(b.w);
;   }
;   __syncthreads();
;   {
;     int n = t >> 3, kk0 = (t & 7) * 8;
;     int ng = ntile * 64 + n, np = ng;
;     if (mode == 1) {
;       if (ng >= 1792) { int j = ng - 1792; int hb = 0; if (j >= 1024) { j -= 1024; hb = 32; } np = 1792 + (j >> 5) * 64 + hb + (j & 31); }
;     } else if (mode == 2) {
;       int j = ng, hb = 0; if (j >= DFF) { j -= DFF; hb = 32; } np = (j >> 5) * 64 + hb + (j & 31);
;     }
; __global__ void __launch_bounds__(NTHREADS, 2) fwd_megakernel(Params p_arg) {
;     ...
;   const int lok_k = (int)xb.local_ok;
;   const int vxcd_k = __builtin_amdgcn_readfirstlane((int)(blockIdx.x & 7) + lok_k * ((int)xb.x - (int)(blockIdx.x & 7)));
;   const int vslot_k = __builtin_amdgcn_readfirstlane((int)(blockIdx.x >> 3) + lok_k * ((int)xb.rank - (int)(blockIdx.x >> 3)));
;     ...
;     for (int rep_ = 0; rep_ < REP_PREP; ++rep_) {
;     ...
;     { PHASE_BEGIN(0);
;   {
;     for (int t = blockIdx.x; t < NLAYER * 3584; t += gridDim.x) {
;       int l = t / 3584, r = t - l * 3584;
;       u16* wl = WB + (size_t)l * WLAYER_E;
;       if (r < 960) { transpose_tile(pk->w_in + (size_t)l * 1024 * INW, wl + WOFF_IN, 1024, INW, r / 60, r % 60, 1, shm, tid); }
;       else if (r < 1088) { r -= 960; transpose_tile(pk->w_a + (size_t)l * 512 * 1024, wl + WOFF_A, 512, 1024, r / 16, r % 16, 0, shm, tid, 1024); }
;       else if (r < 1216) { r -= 1088; transpose_tile(pk->w_b + (size_t)l * 512 * 1024, wl + WOFF_A + 512, 512, 1024, r / 16, r % 16, 0, shm, tid, 1024); }
;       else if (r < 1472) { r -= 1216; transpose_tile(pk->w_o + (size_t)l * 1024 * 1024, wl + WOFF_O, 1024, 1024, r / 16, r % 16, 0, shm, tid); }
;       else if (r < 2880) { r -= 1472; transpose_tile(pk->w_ffn_in + (size_t)l * 1024 * 2 * DFF, wl + WOFF_FI, 1024, 2 * DFF, r / 88, r % 88, 2, shm, tid); }
;       else { r -= 2880; transpose_tile(pk->w_ffn_out + (size_t)l * DFF * 1024, wl + WOFF_FO, DFF, 1024, r / 16, r % 16, 0, shm, tid); }
.LBB0_34:
	s_or_b64 exec, exec, s[34:35]
	v_mov_b32_e32 v3, 0
	s_waitcnt lgkmcnt(0)
	s_barrier
	ds_read_b128 v[4:7], v3
	s_and_b32 s6, s2, 7
	s_waitcnt lgkmcnt(0)
	s_barrier
	v_readfirstlane_b32 s4, v5
	v_readfirstlane_b32 s7, v4
	v_readfirstlane_b32 s16, v7
	v_writelane_b32 v255, s4, 1
	v_readfirstlane_b32 s4, v6
	s_lshr_b32 s10, s16, 16
	s_and_b32 s5, s16, 0xffff
	v_writelane_b32 v255, s4, 2
	v_writelane_b32 v255, s0, 3
	s_mov_b64 s[8:9], s[0:1]
	s_sub_i32 s4, s7, s6
	v_writelane_b32 v255, s1, 4
	v_mbcnt_lo_u32_b32 v0, -1, 0
	v_mbcnt_hi_u32_b32 v0, -1, v0
	s_mul_i32 s4, s10, s4
	v_readlane_b32 s0, v255, 0
	s_add_i32 s6, s4, s6
	s_lshr_b32 s4, s2, 3
	v_add_u32_e32 v0, s0, v0
	s_load_dwordx2 s[0:1], s[8:9], 0x98
	s_load_dwordx2 s[42:43], s[8:9], 0x88
	s_load_dwordx2 s[44:45], s[8:9], 0x80
	s_load_dwordx2 s[46:47], s[8:9], 0x70
	s_load_dwordx2 s[48:49], s[8:9], 0x68
	s_load_dwordx2 s[50:51], s[8:9], 0x60
	s_load_dwordx2 s[52:53], s[8:9], 0x28
	s_sub_i32 s5, s5, s4
	s_mul_i32 s40, s5, s10
	s_add_i32 s40, s40, s4
	v_writelane_b32 v255, s10, 5
	s_cmpk_lt_i32 s2, 0x3800
	v_readfirstlane_b32 s17, v0
	s_cbranch_scc0 .LBB0_59
	v_ashrrev_i32_e32 v1, 3, v0
	v_lshlrev_b32_e32 v2, 3, v0
	v_and_b32_e32 v4, 56, v2
	v_lshlrev_b32_e32 v2, 1, v1
	s_movk_i32 s4, 0x84
	v_mad_u32_u24 v8, v4, s4, v2
	v_mul_lo_u32 v2, v1, s4
	v_lshl_add_u32 v9, v4, 1, v2
	v_and_b32_e32 v10, 31, v1
	s_lshl_b32 s18, s2, 4
	s_lshl_b32 s19, s3, 4
	s_lshl_b32 s20, s2, 8
	s_lshl_b32 s21, s3, 8
	s_mov_b32 s5, 0
	s_movk_i32 s26, 0x1600
	s_movk_i32 s27, 0x5800
	s_movk_i32 s28, 0xaff
	s_movk_i32 s29, 0x3c00
	s_movk_i32 s30, 0x6ff
	v_lshlrev_b32_e32 v2, 2, v4
	v_lshlrev_b32_e32 v4, 1, v4
	v_mov_b32_e32 v11, 0xfffff900
	v_mov_b32_e32 v12, 0xfffff500
	s_lshl_b32 s31, s2, 2
	s_branch .LBB0_38
.LBB0_36:
	s_or_b64 exec, exec, s[14:15]
	v_ashrrev_i32_e32 v7, 31, v6
	ds_read2_b32 v[14:15], v9 offset1:1
	ds_read2_b32 v[16:17], v9 offset0:2 offset1:3
	v_add_u32_e32 v61, 0x4000, v9
	ds_read2_b32 v[44:45], v61 offset1:1
	ds_read2_b32 v[46:47], v61 offset0:2 offset1:3
	v_add_u32_e32 v61, 0x8000, v9
	ds_read2_b32 v[64:65], v61 offset1:1
	ds_read2_b32 v[66:67], v61 offset0:2 offset1:3
	v_add_u32_e32 v61, 0xc000, v9
	ds_read2_b32 v[72:73], v61 offset1:1
	ds_read2_b32 v[74:75], v61 offset0:2 offset1:3
	v_lshlrev_b64 v[6:7], 11, v[6:7]
	v_lshl_add_u64 v[6:7], s[10:11], 0, v[6:7]
	s_ashr_i32 s13, s12, 31
	v_lshl_add_u64 v[6:7], s[12:13], 1, v[6:7]
	v_mov_b32_e32 v5, v3
	v_lshl_add_u64 v[6:7], v[6:7], 0, v[4:5]
	s_waitcnt lgkmcnt(0)
	global_store_dwordx4 v[6:7], v[14:17], off
	s_mul_i32 s54, s58, 1
	s_mov_b32 s55, 0
	v_lshl_add_u64 v[62:63], v[6:7], 0, s[54:55]
	global_store_dwordx4 v[62:63], v[44:47], off
	s_mul_i32 s54, s58, 2
	s_mov_b32 s55, 0
	v_lshl_add_u64 v[62:63], v[6:7], 0, s[54:55]
	global_store_dwordx4 v[62:63], v[64:67], off
	s_mul_i32 s54, s58, 3
	s_mov_b32 s55, 0
	v_lshl_add_u64 v[62:63], v[6:7], 0, s[54:55]
	global_store_dwordx4 v[62:63], v[72:75], off
.LBB0_37:
	v_xor_b32_e32 v8, 0x10000, v8
	v_xor_b32_e32 v9, 0x10000, v9
	s_add_i32 s31, s31, s3
	s_add_i32 s31, s31, s3
	s_add_i32 s31, s31, s3
	s_add_i32 s31, s31, s3
	s_add_i32 s18, s18, s19
	s_add_i32 s20, s20, s21
	s_cmpk_gt_i32 s31, 0x37ff
	s_cbranch_scc1 .LBB0_59
.LBB0_38:
	s_mul_hi_i32 s4, s31, 0x92492493
	s_add_i32 s4, s4, s31
	s_lshr_b32 s10, s4, 31
	s_ashr_i32 s4, s4, 11
	s_add_i32 s12, s4, s10
	s_mul_i32 s4, s12, 0xfffff200
	s_add_i32 s33, s31, s4
	s_ashr_i32 s13, s12, 31
	s_mul_i32 s10, s12, 0x1c40000
	s_mul_hi_i32 s4, s12, 0x1c40000
	s_waitcnt lgkmcnt(0)
	s_add_u32 s10, s0, s10
	s_addc_u32 s11, s1, s4
	s_cmpk_gt_i32 s33, 0x3bf
	s_mov_b64 s[14:15], -1
	s_cbranch_scc0 .LBB0_56
	s_cmpk_gt_u32 s33, 0x43f
	s_cbranch_scc0 .LBB0_53
	s_cmpk_gt_u32 s33, 0x4bf
	s_cbranch_scc0 .LBB0_50
	s_cmpk_gt_u32 s33, 0x5bf
	s_cbranch_scc0 .LBB0_47
	s_cmpk_gt_u32 s33, 0xb3f
	s_cbranch_scc0 .LBB0_44
	s_mov_b64 s[14:15], s[42:43]
	s_mul_i32 s34, s12, 0xb00000
	s_mul_hi_i32 s4, s12, 0xb00000
	s_mul_i32 s35, s12, 0xffffc800
	v_mov_b32_e32 v5, v3
	s_waitcnt lgkmcnt(0)
	s_add_u32 s14, s14, s34
	s_addc_u32 s15, s15, s4
	s_add_i32 s4, s18, s35
	s_andn2_b32 s4, s4, 63
	s_add_i32 s34, s4, 0xffffd300
	v_add_u32_e32 v6, s34, v1
	v_ashrrev_i32_e32 v7, 31, v6
	v_lshlrev_b64 v[6:7], 12, v[6:7]
	v_lshl_add_u64 v[6:7], s[14:15], 0, v[6:7]
	s_and_b32 s14, s20, 0x3c0
	s_lshl_b32 s4, s14, 2
	v_lshl_add_u64 v[6:7], v[6:7], 0, s[4:5]
	v_lshl_add_u64 v[6:7], v[6:7], 0, v[2:3]
	global_load_dwordx4 v[14:17], v[6:7], off
	global_load_dwordx4 v[18:21], v[6:7], off offset:16
	global_load_dwordx4 v[44:47], v[6:7], off offset:256
	global_load_dwordx4 v[48:51], v[6:7], off offset:272
	global_load_dwordx4 v[64:67], v[6:7], off offset:512
	global_load_dwordx4 v[68:71], v[6:7], off offset:528
	global_load_dwordx4 v[72:75], v[6:7], off offset:768
	global_load_dwordx4 v[76:79], v[6:7], off offset:784
	v_mov_b64_e32 v[6:7], s[10:11]
	v_add_u32_e32 v13, s14, v1
	s_mov_b32 s35, s5
	v_mad_i64_i32 v[6:7], s[14:15], v13, s26, v[6:7]
	v_lshl_add_u64 v[6:7], s[34:35], 1, v[6:7]
	v_lshl_add_u64 v[6:7], v[6:7], 0, v[4:5]
	v_add_co_u32_e32 v6, vcc, 0x1680000, v6
	s_mov_b64 s[14:15], 0
	s_nop 0
	v_addc_co_u32_e32 v7, vcc, 0, v7, vcc
	s_waitcnt vmcnt(7)
	v_cvt_pk_bf16_f32 v5, v14, s0
	v_cvt_pk_bf16_f32 v13, v15, s0
	v_cvt_pk_bf16_f32 v14, v16, s0
	v_cvt_pk_bf16_f32 v15, v17, s0
	s_waitcnt vmcnt(6)
	v_cvt_pk_bf16_f32 v16, v18, s0
	v_cvt_pk_bf16_f32 v17, v19, s0
	v_cvt_pk_bf16_f32 v18, v20, s0
	v_cvt_pk_bf16_f32 v19, v21, s0
	ds_write_b16 v8, v5
	ds_write_b16 v8, v13 offset:132
	ds_write_b16 v8, v14 offset:264
	ds_write_b16 v8, v15 offset:396
	ds_write_b16 v8, v16 offset:528
	ds_write_b16 v8, v17 offset:660
	ds_write_b16 v8, v18 offset:792
	ds_write_b16 v8, v19 offset:924
	s_waitcnt vmcnt(5)
; __device__ __forceinline__ u16 f2bf(float a) { return (u16)(pack2(a, 0.f) & 0xffffu); }
;     ...
;     const float4* s = (const float4*)(src + (size_t)(kt * 64 + k) * N + ntile * 64 + n0);
;     float4 a = s[0], b = s[1];
;     tl[(n0 + 0) * 66 + k] = f2bf(a.x); tl[(n0 + 1) * 66 + k] = f2bf(a.y);
;     tl[(n0 + 2) * 66 + k] = f2bf(a.z); tl[(n0 + 3) * 66 + k] = f2bf(a.w);
;     tl[(n0 + 4) * 66 + k] = f2bf(b.x); tl[(n0 + 5) * 66 + k] = f2bf(b.y);
;     tl[(n0 + 6) * 66 + k] = f2bf(b.z); tl[(n0 + 7) * 66 + k] = f2bf(b.w);
;   }
;   __syncthreads();
;   {
;     int n = t >> 3, kk0 = (t & 7) * 8;
;     int ng = ntile * 64 + n, np = ng;
;     if (mode == 1) {
;       if (ng >= 1792) { int j = ng - 1792; int hb = 0; if (j >= 1024) { j -= 1024; hb = 32; } np = 1792 + (j >> 5) * 64 + hb + (j & 31); }
;     } else if (mode == 2) {
;       int j = ng, hb = 0; if (j >= DFF) { j -= DFF; hb = 32; } np = (j >> 5) * 64 + hb + (j & 31);
;     }
;     const uint32_t* r = (const uint32_t*)(tl + n * 66 + kk0);
;     uint4 v = make_uint4(r[0], r[1], r[2], r[3]);
;     *(uint4*)(dst + (size_t)np * dld + kt * 64 + kk0) = v;
	v_cvt_pk_bf16_f32 v52, v44, s0
	v_cvt_pk_bf16_f32 v53, v45, s0
	v_cvt_pk_bf16_f32 v54, v46, s0
	v_cvt_pk_bf16_f32 v55, v47, s0
	s_waitcnt vmcnt(4)
	v_cvt_pk_bf16_f32 v56, v48, s0
	v_cvt_pk_bf16_f32 v57, v49, s0
	v_cvt_pk_bf16_f32 v58, v50, s0
	v_cvt_pk_bf16_f32 v59, v51, s0
	v_add_u32_e32 v60, 0x4000, v8
	ds_write_b16 v60, v52
	ds_write_b16 v60, v53 offset:132
	ds_write_b16 v60, v54 offset:264
	ds_write_b16 v60, v55 offset:396
	ds_write_b16 v60, v56 offset:528
	ds_write_b16 v60, v57 offset:660
	ds_write_b16 v60, v58 offset:792
	ds_write_b16 v60, v59 offset:924
	s_waitcnt vmcnt(3)
	v_cvt_pk_bf16_f32 v52, v64, s0
	v_cvt_pk_bf16_f32 v53, v65, s0
	v_cvt_pk_bf16_f32 v54, v66, s0
	v_cvt_pk_bf16_f32 v55, v67, s0
	s_waitcnt vmcnt(2)
	v_cvt_pk_bf16_f32 v56, v68, s0
	v_cvt_pk_bf16_f32 v57, v69, s0
	v_cvt_pk_bf16_f32 v58, v70, s0
	v_cvt_pk_bf16_f32 v59, v71, s0
	v_add_u32_e32 v60, 0x8000, v8
	ds_write_b16 v60, v52
	ds_write_b16 v60, v53 offset:132
	ds_write_b16 v60, v54 offset:264
	ds_write_b16 v60, v55 offset:396
	ds_write_b16 v60, v56 offset:528
	ds_write_b16 v60, v57 offset:660
	ds_write_b16 v60, v58 offset:792
	ds_write_b16 v60, v59 offset:924
	s_waitcnt vmcnt(1)
	v_cvt_pk_bf16_f32 v52, v72, s0
	v_cvt_pk_bf16_f32 v53, v73, s0
	v_cvt_pk_bf16_f32 v54, v74, s0
	v_cvt_pk_bf16_f32 v55, v75, s0
	s_waitcnt vmcnt(0)
	v_cvt_pk_bf16_f32 v56, v76, s0
	v_cvt_pk_bf16_f32 v57, v77, s0
	v_cvt_pk_bf16_f32 v58, v78, s0
	v_cvt_pk_bf16_f32 v59, v79, s0
	v_add_u32_e32 v60, 0xc000, v8
	ds_write_b16 v60, v52
	ds_write_b16 v60, v53 offset:132
	ds_write_b16 v60, v54 offset:264
	ds_write_b16 v60, v55 offset:396
	ds_write_b16 v60, v56 offset:528
	ds_write_b16 v60, v57 offset:660
	ds_write_b16 v60, v58 offset:792
	ds_write_b16 v60, v59 offset:924
	s_waitcnt lgkmcnt(0)
	s_barrier
	ds_read2_b32 v[14:15], v9 offset1:1
	ds_read2_b32 v[16:17], v9 offset0:2 offset1:3
	v_add_u32_e32 v61, 0x4000, v9
	ds_read2_b32 v[44:45], v61 offset1:1
	ds_read2_b32 v[46:47], v61 offset0:2 offset1:3
	v_add_u32_e32 v61, 0x8000, v9
	ds_read2_b32 v[64:65], v61 offset1:1
	ds_read2_b32 v[66:67], v61 offset0:2 offset1:3
	v_add_u32_e32 v61, 0xc000, v9
	ds_read2_b32 v[72:73], v61 offset1:1
	ds_read2_b32 v[74:75], v61 offset0:2 offset1:3
	s_waitcnt lgkmcnt(0)
	global_store_dwordx4 v[6:7], v[14:17], off
	s_mov_b64 s[54:55], 0x58000
	v_lshl_add_u64 v[62:63], v[6:7], 0, s[54:55]
	global_store_dwordx4 v[62:63], v[44:47], off
	s_mov_b64 s[54:55], 0xb0000
	v_lshl_add_u64 v[62:63], v[6:7], 0, s[54:55]
	global_store_dwordx4 v[62:63], v[64:67], off
	s_mov_b64 s[54:55], 0x108000
	v_lshl_add_u64 v[62:63], v[6:7], 0, s[54:55]
	global_store_dwordx4 v[62:63], v[72:75], off
; __device__ __forceinline__ u16 f2bf(float a) { return (u16)(pack2(a, 0.f) & 0xffffu); }
;     ...
;   {
;     int k = t >> 3, n0 = (t & 7) * 8;
;     const float4* s = (const float4*)(src + (size_t)(kt * 64 + k) * N + ntile * 64 + n0);
;     float4 a = s[0], b = s[1];
;     tl[(n0 + 0) * 66 + k] = f2bf(a.x); tl[(n0 + 1) * 66 + k] = f2bf(a.y);
;     tl[(n0 + 2) * 66 + k] = f2bf(a.z); tl[(n0 + 3) * 66 + k] = f2bf(a.w);
;     tl[(n0 + 4) * 66 + k] = f2bf(b.x); tl[(n0 + 5) * 66 + k] = f2bf(b.y);
;     tl[(n0 + 6) * 66 + k] = f2bf(b.z); tl[(n0 + 7) * 66 + k] = f2bf(b.w);
;   }
;   __syncthreads();
;   {
;     int n = t >> 3, kk0 = (t & 7) * 8;
;     int ng = ntile * 64 + n, np = ng;
;     if (mode == 1) {
;       if (ng >= 1792) { int j = ng - 1792; int hb = 0; if (j >= 1024) { j -= 1024; hb = 32; } np = 1792 + (j >> 5) * 64 + hb + (j & 31); }
;     } else if (mode == 2) {
;       int j = ng, hb = 0; if (j >= DFF) { j -= DFF; hb = 32; } np = (j >> 5) * 64 + hb + (j & 31);
;     }
;     const uint32_t* r = (const uint32_t*)(tl + n * 66 + kk0);
;     uint4 v = make_uint4(r[0], r[1], r[2], r[3]);
;     *(uint4*)(dst + (size_t)np * dld + kt * 64 + kk0) = v;
; __global__ void __launch_bounds__(NTHREADS, 2) fwd_megakernel(Params p_arg) {
;     ...
;       else if (r < 2880) { r -= 1472; transpose_tile(pk->w_ffn_in + (size_t)l * 1024 * 2 * DFF, wl + WOFF_FI, 1024, 2 * DFF, r / 88, r % 88, 2, shm, tid); }
.LBB0_44:
	s_andn2_b64 vcc, exec, s[14:15]
	s_cbranch_vccnz .LBB0_46
	s_mov_b64 s[14:15], s[44:45]
	s_mul_i32 s34, s12, 0x1600000
	s_mul_hi_i32 s4, s12, 0x1600000
	s_waitcnt lgkmcnt(0)
	s_add_u32 s14, s14, s34
	s_addc_u32 s15, s15, s4
	s_add_i32 s4, s33, 0xfa40
	s_and_b32 s34, s4, 0xffff
	s_mul_i32 s34, s34, 0xba2f
	s_lshr_b32 s35, s34, 16
	s_lshr_b32 s34, s34, 22
	s_mulk_i32 s34, 0x58
	s_sub_i32 s4, s4, s34
	s_and_b32 s34, s35, 0xffc0
	v_add_u32_e32 v5, s34, v1
	v_mov_b64_e32 v[6:7], s[14:15]
	v_mad_i64_i32 v[6:7], s[14:15], v5, s27, v[6:7]
	s_lshl_b32 s4, s4, 6
	s_and_b32 s14, s4, 0xffc0
	s_lshl_b32 s4, s14, 2
	v_lshl_add_u64 v[6:7], v[6:7], 0, s[4:5]
	v_lshl_add_u64 v[6:7], v[6:7], 0, v[2:3]
	global_load_dwordx4 v[14:17], v[6:7], off
	global_load_dwordx4 v[18:21], v[6:7], off offset:16
	global_load_dwordx4 v[44:47], v[6:7], off offset:256
	global_load_dwordx4 v[48:51], v[6:7], off offset:272
	global_load_dwordx4 v[64:67], v[6:7], off offset:512
	global_load_dwordx4 v[68:71], v[6:7], off offset:528
	global_load_dwordx4 v[72:75], v[6:7], off offset:768
	global_load_dwordx4 v[76:79], v[6:7], off offset:784
	v_add_u32_e32 v6, s14, v1
	v_add_u32_e32 v7, 0xfffff500, v6
	v_cmp_lt_i32_e32 vcc, s28, v6
	s_lshl_b32 s4, s34, 1
	v_mov_b32_e32 v5, v3
	v_cndmask_b32_e32 v6, v6, v7, vcc
	v_lshlrev_b32_e32 v7, 1, v6
	v_cndmask_b32_e64 v13, 0, 32, vcc
	v_and_b32_e32 v6, 31, v6
	v_and_b32_e32 v7, 0xffffffc0, v7
	v_or3_b32 v6, v6, v13, v7
	v_ashrrev_i32_e32 v7, 31, v6
	v_lshlrev_b64 v[6:7], 11, v[6:7]
	v_lshl_add_u64 v[6:7], s[10:11], 0, v[6:7]
	v_lshl_add_u64 v[6:7], v[6:7], 0, s[4:5]
	v_lshl_add_u64 v[6:7], v[6:7], 0, v[4:5]
	v_add_co_u32_e32 v6, vcc, 0xb80000, v6
	s_waitcnt vmcnt(7)
	v_cvt_pk_bf16_f32 v5, v14, s0
	v_cvt_pk_bf16_f32 v13, v15, s0
	v_cvt_pk_bf16_f32 v14, v16, s0
	v_cvt_pk_bf16_f32 v15, v17, s0
	s_waitcnt vmcnt(6)
	v_cvt_pk_bf16_f32 v16, v18, s0
	v_cvt_pk_bf16_f32 v17, v19, s0
	v_cvt_pk_bf16_f32 v18, v20, s0
	v_cvt_pk_bf16_f32 v19, v21, s0
	ds_write_b16 v8, v5
	ds_write_b16 v8, v13 offset:132
	ds_write_b16 v8, v14 offset:264
	ds_write_b16 v8, v15 offset:396
	ds_write_b16 v8, v16 offset:528
	ds_write_b16 v8, v17 offset:660
	ds_write_b16 v8, v18 offset:792
	ds_write_b16 v8, v19 offset:924
	s_waitcnt vmcnt(5)
	v_cvt_pk_bf16_f32 v52, v44, s0
	v_cvt_pk_bf16_f32 v53, v45, s0
	v_cvt_pk_bf16_f32 v54, v46, s0
	v_cvt_pk_bf16_f32 v55, v47, s0
	s_waitcnt vmcnt(4)
	v_cvt_pk_bf16_f32 v56, v48, s0
	v_cvt_pk_bf16_f32 v57, v49, s0
	v_cvt_pk_bf16_f32 v58, v50, s0
	v_cvt_pk_bf16_f32 v59, v51, s0
	v_add_u32_e32 v60, 0x4000, v8
	ds_write_b16 v60, v52
	ds_write_b16 v60, v53 offset:132
	ds_write_b16 v60, v54 offset:264
	ds_write_b16 v60, v55 offset:396
	ds_write_b16 v60, v56 offset:528
	ds_write_b16 v60, v57 offset:660
	ds_write_b16 v60, v58 offset:792
	ds_write_b16 v60, v59 offset:924
	s_waitcnt vmcnt(3)
	v_cvt_pk_bf16_f32 v52, v64, s0
	v_cvt_pk_bf16_f32 v53, v65, s0
	v_cvt_pk_bf16_f32 v54, v66, s0
	v_cvt_pk_bf16_f32 v55, v67, s0
	s_waitcnt vmcnt(2)
	v_cvt_pk_bf16_f32 v56, v68, s0
	v_cvt_pk_bf16_f32 v57, v69, s0
	v_cvt_pk_bf16_f32 v58, v70, s0
	v_cvt_pk_bf16_f32 v59, v71, s0
	v_add_u32_e32 v60, 0x8000, v8
	ds_write_b16 v60, v52
	ds_write_b16 v60, v53 offset:132
	ds_write_b16 v60, v54 offset:264
	ds_write_b16 v60, v55 offset:396
	ds_write_b16 v60, v56 offset:528
	ds_write_b16 v60, v57 offset:660
	ds_write_b16 v60, v58 offset:792
	ds_write_b16 v60, v59 offset:924
	s_waitcnt vmcnt(1)
	v_cvt_pk_bf16_f32 v52, v72, s0
	v_cvt_pk_bf16_f32 v53, v73, s0
	v_cvt_pk_bf16_f32 v54, v74, s0
	v_cvt_pk_bf16_f32 v55, v75, s0
	s_waitcnt vmcnt(0)
	v_cvt_pk_bf16_f32 v56, v76, s0
	v_cvt_pk_bf16_f32 v57, v77, s0
	v_cvt_pk_bf16_f32 v58, v78, s0
	v_cvt_pk_bf16_f32 v59, v79, s0
	v_add_u32_e32 v60, 0xc000, v8
	ds_write_b16 v60, v52
	ds_write_b16 v60, v53 offset:132
	ds_write_b16 v60, v54 offset:264
	ds_write_b16 v60, v55 offset:396
	ds_write_b16 v60, v56 offset:528
	ds_write_b16 v60, v57 offset:660
	ds_write_b16 v60, v58 offset:792
	ds_write_b16 v60, v59 offset:924
	s_waitcnt lgkmcnt(0)
	s_barrier
	ds_read2_b32 v[14:15], v9 offset1:1
	ds_read2_b32 v[16:17], v9 offset0:2 offset1:3
	v_add_u32_e32 v61, 0x4000, v9
	ds_read2_b32 v[44:45], v61 offset1:1
	ds_read2_b32 v[46:47], v61 offset0:2 offset1:3
	v_add_u32_e32 v61, 0x8000, v9
	ds_read2_b32 v[64:65], v61 offset1:1
	ds_read2_b32 v[66:67], v61 offset0:2 offset1:3
	v_add_u32_e32 v61, 0xc000, v9
	ds_read2_b32 v[72:73], v61 offset1:1
	ds_read2_b32 v[74:75], v61 offset0:2 offset1:3
	v_addc_co_u32_e32 v7, vcc, 0, v7, vcc
	s_waitcnt lgkmcnt(0)
	global_store_dwordx4 v[6:7], v[14:17], off
	s_mov_b64 s[54:55], 0x40000
	v_lshl_add_u64 v[62:63], v[6:7], 0, s[54:55]
	global_store_dwordx4 v[62:63], v[44:47], off
	s_mov_b64 s[54:55], 0x80000
	v_lshl_add_u64 v[62:63], v[6:7], 0, s[54:55]
	global_store_dwordx4 v[62:63], v[64:67], off
	s_mov_b64 s[54:55], 0xc0000
	v_lshl_add_u64 v[62:63], v[6:7], 0, s[54:55]
	global_store_dwordx4 v[62:63], v[72:75], off

; __device__ __forceinline__ u16 f2bf(float a) { return (u16)(pack2(a, 0.f) & 0xffffu); }
;     ...
;   {
;     int k = t >> 3, n0 = (t & 7) * 8;
;     const float4* s = (const float4*)(src + (size_t)(kt * 64 + k) * N + ntile * 64 + n0);
;     float4 a = s[0], b = s[1];
;     tl[(n0 + 0) * 66 + k] = f2bf(a.x); tl[(n0 + 1) * 66 + k] = f2bf(a.y);
;     tl[(n0 + 2) * 66 + k] = f2bf(a.z); tl[(n0 + 3) * 66 + k] = f2bf(a.w);
;     tl[(n0 + 4) * 66 + k] = f2bf(b.x); tl[(n0 + 5) * 66 + k] = f2bf(b.y);
;     tl[(n0 + 6) * 66 + k] = f2bf(b.z); tl[(n0 + 7) * 66 + k] = f2bf(b.w);
;   }
;   __syncthreads();
;   {
;     int n = t >> 3, kk0 = (t & 7) * 8;
;     int ng = ntile * 64 + n, np = ng;
;     if (mode == 1) {
;       if (ng >= 1792) { int j = ng - 1792; int hb = 0; if (j >= 1024) { j -= 1024; hb = 32; } np = 1792 + (j >> 5) * 64 + hb + (j & 31); }
;     } else if (mode == 2) {
;       int j = ng, hb = 0; if (j >= DFF) { j -= DFF; hb = 32; } np = (j >> 5) * 64 + hb + (j & 31);
;     }
;     const uint32_t* r = (const uint32_t*)(tl + n * 66 + kk0);
;     uint4 v = make_uint4(r[0], r[1], r[2], r[3]);
;     *(uint4*)(dst + (size_t)np * dld + kt * 64 + kk0) = v;
; __global__ void __launch_bounds__(NTHREADS, 2) fwd_megakernel(Params p_arg) {
;     ...
;       else if (r < 1472) { r -= 1216; transpose_tile(pk->w_o + (size_t)l * 1024 * 1024, wl + WOFF_O, 1024, 1024, r / 16, r % 16, 0, shm, tid); }
.LBB0_47:
	s_andn2_b64 vcc, exec, s[14:15]
	s_cbranch_vccnz .LBB0_49
	s_mov_b64 s[14:15], s[46:47]
	s_lshl_b64 s[34:35], s[12:13], 22
	s_mul_i32 s4, s12, 0xffffc800
	v_mov_b32_e32 v5, v3
	s_waitcnt lgkmcnt(0)
	s_add_u32 s14, s14, s34
	s_addc_u32 s15, s15, s35
	s_add_i32 s4, s18, s4
	s_and_b32 s4, s4, 0x1fc0
	s_add_i32 s34, s4, 0xffffed00
	v_add_u32_e32 v6, s34, v1
	v_ashrrev_i32_e32 v7, 31, v6
	s_and_b32 s36, s20, 0x3c0
	v_lshlrev_b64 v[6:7], 12, v[6:7]
	v_lshl_add_u64 v[6:7], s[14:15], 0, v[6:7]
	s_lshl_b32 s4, s36, 2
	v_lshl_add_u64 v[6:7], v[6:7], 0, s[4:5]
	v_lshl_add_u64 v[6:7], v[6:7], 0, v[2:3]
	global_load_dwordx4 v[14:17], v[6:7], off
	global_load_dwordx4 v[18:21], v[6:7], off offset:16
	global_load_dwordx4 v[44:47], v[6:7], off offset:256
	global_load_dwordx4 v[48:51], v[6:7], off offset:272
	global_load_dwordx4 v[64:67], v[6:7], off offset:512
	global_load_dwordx4 v[68:71], v[6:7], off offset:528
	global_load_dwordx4 v[72:75], v[6:7], off offset:768
	global_load_dwordx4 v[76:79], v[6:7], off offset:784
	v_add_u32_e32 v6, s36, v1
	v_ashrrev_i32_e32 v7, 31, v6
	v_lshlrev_b64 v[6:7], 11, v[6:7]
	s_mov_b32 s35, s5
	v_lshl_add_u64 v[6:7], s[10:11], 0, v[6:7]
	v_lshl_add_u64 v[6:7], s[34:35], 1, v[6:7]
	v_lshl_add_u64 v[6:7], v[6:7], 0, v[4:5]
	v_add_co_u32_e32 v6, vcc, 0x980000, v6
	s_waitcnt vmcnt(7)
	v_cvt_pk_bf16_f32 v5, v14, s0
	v_cvt_pk_bf16_f32 v13, v15, s0
	v_cvt_pk_bf16_f32 v14, v16, s0
	v_cvt_pk_bf16_f32 v15, v17, s0
	s_waitcnt vmcnt(6)
	v_cvt_pk_bf16_f32 v16, v18, s0
	v_cvt_pk_bf16_f32 v17, v19, s0
	v_cvt_pk_bf16_f32 v18, v20, s0
	v_cvt_pk_bf16_f32 v19, v21, s0
	ds_write_b16 v8, v5
	ds_write_b16 v8, v13 offset:132
	ds_write_b16 v8, v14 offset:264
	ds_write_b16 v8, v15 offset:396
	ds_write_b16 v8, v16 offset:528
	ds_write_b16 v8, v17 offset:660
	ds_write_b16 v8, v18 offset:792
	ds_write_b16 v8, v19 offset:924
	s_waitcnt vmcnt(5)
	v_cvt_pk_bf16_f32 v52, v44, s0
	v_cvt_pk_bf16_f32 v53, v45, s0
	v_cvt_pk_bf16_f32 v54, v46, s0
	v_cvt_pk_bf16_f32 v55, v47, s0
	s_waitcnt vmcnt(4)
	v_cvt_pk_bf16_f32 v56, v48, s0
	v_cvt_pk_bf16_f32 v57, v49, s0
	v_cvt_pk_bf16_f32 v58, v50, s0
	v_cvt_pk_bf16_f32 v59, v51, s0
	v_add_u32_e32 v60, 0x4000, v8
	ds_write_b16 v60, v52
	ds_write_b16 v60, v53 offset:132
	ds_write_b16 v60, v54 offset:264
	ds_write_b16 v60, v55 offset:396
	ds_write_b16 v60, v56 offset:528
	ds_write_b16 v60, v57 offset:660
	ds_write_b16 v60, v58 offset:792
	ds_write_b16 v60, v59 offset:924
	s_waitcnt vmcnt(3)
	v_cvt_pk_bf16_f32 v52, v64, s0
	v_cvt_pk_bf16_f32 v53, v65, s0
	v_cvt_pk_bf16_f32 v54, v66, s0
	v_cvt_pk_bf16_f32 v55, v67, s0
	s_waitcnt vmcnt(2)
	v_cvt_pk_bf16_f32 v56, v68, s0
	v_cvt_pk_bf16_f32 v57, v69, s0
	v_cvt_pk_bf16_f32 v58, v70, s0
	v_cvt_pk_bf16_f32 v59, v71, s0
	v_add_u32_e32 v60, 0x8000, v8
	ds_write_b16 v60, v52
	ds_write_b16 v60, v53 offset:132
	ds_write_b16 v60, v54 offset:264
	ds_write_b16 v60, v55 offset:396
	ds_write_b16 v60, v56 offset:528
	ds_write_b16 v60, v57 offset:660
	ds_write_b16 v60, v58 offset:792
	ds_write_b16 v60, v59 offset:924
	s_waitcnt vmcnt(1)
	v_cvt_pk_bf16_f32 v52, v72, s0
	v_cvt_pk_bf16_f32 v53, v73, s0
	v_cvt_pk_bf16_f32 v54, v74, s0
	v_cvt_pk_bf16_f32 v55, v75, s0
	s_waitcnt vmcnt(0)
	v_cvt_pk_bf16_f32 v56, v76, s0
	v_cvt_pk_bf16_f32 v57, v77, s0
	v_cvt_pk_bf16_f32 v58, v78, s0
	v_cvt_pk_bf16_f32 v59, v79, s0
	v_add_u32_e32 v60, 0xc000, v8
	ds_write_b16 v60, v52
	ds_write_b16 v60, v53 offset:132
	ds_write_b16 v60, v54 offset:264
	ds_write_b16 v60, v55 offset:396
	ds_write_b16 v60, v56 offset:528
	ds_write_b16 v60, v57 offset:660
	ds_write_b16 v60, v58 offset:792
	ds_write_b16 v60, v59 offset:924
	s_waitcnt lgkmcnt(0)
	s_barrier
	ds_read2_b32 v[14:15], v9 offset1:1
	ds_read2_b32 v[16:17], v9 offset0:2 offset1:3
	v_add_u32_e32 v61, 0x4000, v9
	ds_read2_b32 v[44:45], v61 offset1:1
	ds_read2_b32 v[46:47], v61 offset0:2 offset1:3
	v_add_u32_e32 v61, 0x8000, v9
	ds_read2_b32 v[64:65], v61 offset1:1
	ds_read2_b32 v[66:67], v61 offset0:2 offset1:3
	v_add_u32_e32 v61, 0xc000, v9
	ds_read2_b32 v[72:73], v61 offset1:1
	ds_read2_b32 v[74:75], v61 offset0:2 offset1:3
	v_addc_co_u32_e32 v7, vcc, 0, v7, vcc
	s_waitcnt lgkmcnt(0)
	global_store_dwordx4 v[6:7], v[14:17], off
	s_mov_b64 s[54:55], 0x20000
	v_lshl_add_u64 v[62:63], v[6:7], 0, s[54:55]
	global_store_dwordx4 v[62:63], v[44:47], off
	s_mov_b64 s[54:55], 0x40000
	v_lshl_add_u64 v[62:63], v[6:7], 0, s[54:55]
	global_store_dwordx4 v[62:63], v[64:67], off
	s_mov_b64 s[54:55], 0x60000
	v_lshl_add_u64 v[62:63], v[6:7], 0, s[54:55]
	global_store_dwordx4 v[62:63], v[72:75], off

; __device__ __forceinline__ u16 f2bf(float a) { return (u16)(pack2(a, 0.f) & 0xffffu); }
;     ...
;   {
;     int k = t >> 3, n0 = (t & 7) * 8;
;     const float4* s = (const float4*)(src + (size_t)(kt * 64 + k) * N + ntile * 64 + n0);
;     float4 a = s[0], b = s[1];
;     tl[(n0 + 0) * 66 + k] = f2bf(a.x); tl[(n0 + 1) * 66 + k] = f2bf(a.y);
;     tl[(n0 + 2) * 66 + k] = f2bf(a.z); tl[(n0 + 3) * 66 + k] = f2bf(a.w);
;     tl[(n0 + 4) * 66 + k] = f2bf(b.x); tl[(n0 + 5) * 66 + k] = f2bf(b.y);
;     tl[(n0 + 6) * 66 + k] = f2bf(b.z); tl[(n0 + 7) * 66 + k] = f2bf(b.w);
;   }
;   __syncthreads();
;   {
;     int n = t >> 3, kk0 = (t & 7) * 8;
;     int ng = ntile * 64 + n, np = ng;
;     if (mode == 1) {
;       if (ng >= 1792) { int j = ng - 1792; int hb = 0; if (j >= 1024) { j -= 1024; hb = 32; } np = 1792 + (j >> 5) * 64 + hb + (j & 31); }
;     } else if (mode == 2) {
;       int j = ng, hb = 0; if (j >= DFF) { j -= DFF; hb = 32; } np = (j >> 5) * 64 + hb + (j & 31);
;     }
;     const uint32_t* r = (const uint32_t*)(tl + n * 66 + kk0);
;     uint4 v = make_uint4(r[0], r[1], r[2], r[3]);
;     *(uint4*)(dst + (size_t)np * dld + kt * 64 + kk0) = v;
; __global__ void __launch_bounds__(NTHREADS, 2) fwd_megakernel(Params p_arg) {
;     ...
;       else if (r < 1216) { r -= 1088; transpose_tile(pk->w_b + (size_t)l * 512 * 1024, wl + WOFF_A + 512, 512, 1024, r / 16, r % 16, 0, shm, tid, 1024); }
.LBB0_50:
	s_andn2_b64 vcc, exec, s[14:15]
	s_cbranch_vccnz .LBB0_52
	s_mov_b64 s[14:15], s[48:49]
	s_lshl_b64 s[34:35], s[12:13], 21
	s_mul_i32 s4, s12, 0xffffc800
	v_mov_b32_e32 v5, v3
	s_waitcnt lgkmcnt(0)
	s_add_u32 s14, s14, s34
	s_addc_u32 s15, s15, s35
	s_add_i32 s4, s18, s4
	s_and_b32 s4, s4, 0x1fc0
	s_add_i32 s34, s4, 0xffffef00
	v_add_u32_e32 v6, s34, v1
	v_ashrrev_i32_e32 v7, 31, v6
	s_and_b32 s36, s20, 0x3c0
	v_lshlrev_b64 v[6:7], 12, v[6:7]
	v_lshl_add_u64 v[6:7], s[14:15], 0, v[6:7]
	s_lshl_b32 s4, s36, 2
	v_lshl_add_u64 v[6:7], v[6:7], 0, s[4:5]
	v_lshl_add_u64 v[6:7], v[6:7], 0, v[2:3]
	global_load_dwordx4 v[14:17], v[6:7], off
	global_load_dwordx4 v[18:21], v[6:7], off offset:16
	global_load_dwordx4 v[44:47], v[6:7], off offset:256
	global_load_dwordx4 v[48:51], v[6:7], off offset:272
	global_load_dwordx4 v[64:67], v[6:7], off offset:512
	global_load_dwordx4 v[68:71], v[6:7], off offset:528
	global_load_dwordx4 v[72:75], v[6:7], off offset:768
	global_load_dwordx4 v[76:79], v[6:7], off offset:784
	v_add_u32_e32 v6, s36, v1
	v_ashrrev_i32_e32 v7, 31, v6
	v_lshlrev_b64 v[6:7], 11, v[6:7]
	s_mov_b32 s35, s5
	v_lshl_add_u64 v[6:7], s[10:11], 0, v[6:7]
	v_lshl_add_u64 v[6:7], s[34:35], 1, v[6:7]
	v_lshl_add_u64 v[6:7], v[6:7], 0, v[4:5]
	v_add_co_u32_e32 v6, vcc, 0x780000, v6
	s_waitcnt vmcnt(7)
	v_cvt_pk_bf16_f32 v5, v14, s0
	v_cvt_pk_bf16_f32 v13, v15, s0
	v_cvt_pk_bf16_f32 v14, v16, s0
	v_cvt_pk_bf16_f32 v15, v17, s0
	s_waitcnt vmcnt(6)
	v_cvt_pk_bf16_f32 v16, v18, s0
	v_cvt_pk_bf16_f32 v17, v19, s0
	v_cvt_pk_bf16_f32 v18, v20, s0
	v_cvt_pk_bf16_f32 v19, v21, s0
	ds_write_b16 v8, v5
	ds_write_b16 v8, v13 offset:132
	ds_write_b16 v8, v14 offset:264
	ds_write_b16 v8, v15 offset:396
	ds_write_b16 v8, v16 offset:528
	ds_write_b16 v8, v17 offset:660
	ds_write_b16 v8, v18 offset:792
	ds_write_b16 v8, v19 offset:924
	s_waitcnt vmcnt(5)
	v_cvt_pk_bf16_f32 v52, v44, s0
	v_cvt_pk_bf16_f32 v53, v45, s0
	v_cvt_pk_bf16_f32 v54, v46, s0
	v_cvt_pk_bf16_f32 v55, v47, s0
	s_waitcnt vmcnt(4)
	v_cvt_pk_bf16_f32 v56, v48, s0
	v_cvt_pk_bf16_f32 v57, v49, s0
	v_cvt_pk_bf16_f32 v58, v50, s0
	v_cvt_pk_bf16_f32 v59, v51, s0
	v_add_u32_e32 v60, 0x4000, v8
	ds_write_b16 v60, v52
	ds_write_b16 v60, v53 offset:132
	ds_write_b16 v60, v54 offset:264
	ds_write_b16 v60, v55 offset:396
	ds_write_b16 v60, v56 offset:528
	ds_write_b16 v60, v57 offset:660
	ds_write_b16 v60, v58 offset:792
	ds_write_b16 v60, v59 offset:924
	s_waitcnt vmcnt(3)
	v_cvt_pk_bf16_f32 v52, v64, s0
	v_cvt_pk_bf16_f32 v53, v65, s0
	v_cvt_pk_bf16_f32 v54, v66, s0
	v_cvt_pk_bf16_f32 v55, v67, s0
	s_waitcnt vmcnt(2)
	v_cvt_pk_bf16_f32 v56, v68, s0
	v_cvt_pk_bf16_f32 v57, v69, s0
	v_cvt_pk_bf16_f32 v58, v70, s0
	v_cvt_pk_bf16_f32 v59, v71, s0
	v_add_u32_e32 v60, 0x8000, v8
	ds_write_b16 v60, v52
	ds_write_b16 v60, v53 offset:132
	ds_write_b16 v60, v54 offset:264
	ds_write_b16 v60, v55 offset:396
	ds_write_b16 v60, v56 offset:528
	ds_write_b16 v60, v57 offset:660
	ds_write_b16 v60, v58 offset:792
	ds_write_b16 v60, v59 offset:924
	s_waitcnt vmcnt(1)
	v_cvt_pk_bf16_f32 v52, v72, s0
	v_cvt_pk_bf16_f32 v53, v73, s0
	v_cvt_pk_bf16_f32 v54, v74, s0
	v_cvt_pk_bf16_f32 v55, v75, s0
	s_waitcnt vmcnt(0)
	v_cvt_pk_bf16_f32 v56, v76, s0
	v_cvt_pk_bf16_f32 v57, v77, s0
	v_cvt_pk_bf16_f32 v58, v78, s0
	v_cvt_pk_bf16_f32 v59, v79, s0
	v_add_u32_e32 v60, 0xc000, v8
	ds_write_b16 v60, v52
	ds_write_b16 v60, v53 offset:132
	ds_write_b16 v60, v54 offset:264
	ds_write_b16 v60, v55 offset:396
	ds_write_b16 v60, v56 offset:528
	ds_write_b16 v60, v57 offset:660
	ds_write_b16 v60, v58 offset:792
	ds_write_b16 v60, v59 offset:924
	s_waitcnt lgkmcnt(0)
	s_barrier
	ds_read2_b32 v[14:15], v9 offset1:1
	ds_read2_b32 v[16:17], v9 offset0:2 offset1:3
	v_add_u32_e32 v61, 0x4000, v9
	ds_read2_b32 v[44:45], v61 offset1:1
	ds_read2_b32 v[46:47], v61 offset0:2 offset1:3
	v_add_u32_e32 v61, 0x8000, v9
	ds_read2_b32 v[64:65], v61 offset1:1
	ds_read2_b32 v[66:67], v61 offset0:2 offset1:3
	v_add_u32_e32 v61, 0xc000, v9
	ds_read2_b32 v[72:73], v61 offset1:1
	ds_read2_b32 v[74:75], v61 offset0:2 offset1:3
	v_addc_co_u32_e32 v7, vcc, 0, v7, vcc
	s_waitcnt lgkmcnt(0)
	global_store_dwordx4 v[6:7], v[14:17], off offset:1024
	s_mov_b64 s[54:55], 0x20000
	v_lshl_add_u64 v[62:63], v[6:7], 0, s[54:55]
	global_store_dwordx4 v[62:63], v[44:47], off offset:1024
	s_mov_b64 s[54:55], 0x40000
	v_lshl_add_u64 v[62:63], v[6:7], 0, s[54:55]
	global_store_dwordx4 v[62:63], v[64:67], off offset:1024
	s_mov_b64 s[54:55], 0x60000
	v_lshl_add_u64 v[62:63], v[6:7], 0, s[54:55]
	global_store_dwordx4 v[62:63], v[72:75], off offset:1024

; __device__ __forceinline__ u16 f2bf(float a) { return (u16)(pack2(a, 0.f) & 0xffffu); }
;     ...
;   {
;     int k = t >> 3, n0 = (t & 7) * 8;
;     const float4* s = (const float4*)(src + (size_t)(kt * 64 + k) * N + ntile * 64 + n0);
;     float4 a = s[0], b = s[1];
;     tl[(n0 + 0) * 66 + k] = f2bf(a.x); tl[(n0 + 1) * 66 + k] = f2bf(a.y);
;     tl[(n0 + 2) * 66 + k] = f2bf(a.z); tl[(n0 + 3) * 66 + k] = f2bf(a.w);
;     tl[(n0 + 4) * 66 + k] = f2bf(b.x); tl[(n0 + 5) * 66 + k] = f2bf(b.y);
;     tl[(n0 + 6) * 66 + k] = f2bf(b.z); tl[(n0 + 7) * 66 + k] = f2bf(b.w);
;   }
;   __syncthreads();
;   {
;     int n = t >> 3, kk0 = (t & 7) * 8;
;     int ng = ntile * 64 + n, np = ng;
;     if (mode == 1) {
;       if (ng >= 1792) { int j = ng - 1792; int hb = 0; if (j >= 1024) { j -= 1024; hb = 32; } np = 1792 + (j >> 5) * 64 + hb + (j & 31); }
;     } else if (mode == 2) {
;       int j = ng, hb = 0; if (j >= DFF) { j -= DFF; hb = 32; } np = (j >> 5) * 64 + hb + (j & 31);
;     }
;     const uint32_t* r = (const uint32_t*)(tl + n * 66 + kk0);
;     uint4 v = make_uint4(r[0], r[1], r[2], r[3]);
;     *(uint4*)(dst + (size_t)np * dld + kt * 64 + kk0) = v;
; __global__ void __launch_bounds__(NTHREADS, 2) fwd_megakernel(Params p_arg) {
;     ...
;       else if (r < 1088) { r -= 960; transpose_tile(pk->w_a + (size_t)l * 512 * 1024, wl + WOFF_A, 512, 1024, r / 16, r % 16, 0, shm, tid, 1024); }
.LBB0_53:
	s_andn2_b64 vcc, exec, s[14:15]
	s_cbranch_vccnz .LBB0_55
	s_mov_b64 s[14:15], s[50:51]
	s_lshl_b64 s[34:35], s[12:13], 21
	s_mul_i32 s4, s12, 0xffffc800
	v_mov_b32_e32 v5, v3
	s_waitcnt lgkmcnt(0)
	s_add_u32 s14, s14, s34
	s_addc_u32 s15, s15, s35
	s_add_i32 s4, s18, s4
	s_and_b32 s4, s4, 0x1fc0
	s_add_i32 s34, s4, 0xfffff100
	v_add_u32_e32 v6, s34, v1
	v_ashrrev_i32_e32 v7, 31, v6
	s_and_b32 s13, s20, 0x3c0
	v_lshlrev_b64 v[6:7], 12, v[6:7]
	v_lshl_add_u64 v[6:7], s[14:15], 0, v[6:7]
	s_lshl_b32 s4, s13, 2
	v_lshl_add_u64 v[6:7], v[6:7], 0, s[4:5]
	v_lshl_add_u64 v[6:7], v[6:7], 0, v[2:3]
	global_load_dwordx4 v[14:17], v[6:7], off
	global_load_dwordx4 v[18:21], v[6:7], off offset:16
	global_load_dwordx4 v[44:47], v[6:7], off offset:256
	global_load_dwordx4 v[48:51], v[6:7], off offset:272
	global_load_dwordx4 v[64:67], v[6:7], off offset:512
	global_load_dwordx4 v[68:71], v[6:7], off offset:528
	global_load_dwordx4 v[72:75], v[6:7], off offset:768
	global_load_dwordx4 v[76:79], v[6:7], off offset:784
	v_add_u32_e32 v6, s13, v1
	v_ashrrev_i32_e32 v7, 31, v6
	v_lshlrev_b64 v[6:7], 11, v[6:7]
	s_mov_b32 s35, s5
	v_lshl_add_u64 v[6:7], s[10:11], 0, v[6:7]
	v_lshl_add_u64 v[6:7], s[34:35], 1, v[6:7]
	v_lshl_add_u64 v[6:7], v[6:7], 0, v[4:5]
	v_add_co_u32_e32 v6, vcc, 0x780000, v6
	s_waitcnt vmcnt(7)
	v_cvt_pk_bf16_f32 v5, v14, s0
	v_cvt_pk_bf16_f32 v13, v15, s0
	v_cvt_pk_bf16_f32 v14, v16, s0
	v_cvt_pk_bf16_f32 v15, v17, s0
	s_waitcnt vmcnt(6)
	v_cvt_pk_bf16_f32 v16, v18, s0
	v_cvt_pk_bf16_f32 v17, v19, s0
	v_cvt_pk_bf16_f32 v18, v20, s0
	v_cvt_pk_bf16_f32 v19, v21, s0
	ds_write_b16 v8, v5
	ds_write_b16 v8, v13 offset:132
	ds_write_b16 v8, v14 offset:264
	ds_write_b16 v8, v15 offset:396
	ds_write_b16 v8, v16 offset:528
	ds_write_b16 v8, v17 offset:660
	ds_write_b16 v8, v18 offset:792
	ds_write_b16 v8, v19 offset:924
	s_waitcnt vmcnt(5)
	v_cvt_pk_bf16_f32 v52, v44, s0
	v_cvt_pk_bf16_f32 v53, v45, s0
	v_cvt_pk_bf16_f32 v54, v46, s0
	v_cvt_pk_bf16_f32 v55, v47, s0
	s_waitcnt vmcnt(4)
	v_cvt_pk_bf16_f32 v56, v48, s0
	v_cvt_pk_bf16_f32 v57, v49, s0
	v_cvt_pk_bf16_f32 v58, v50, s0
	v_cvt_pk_bf16_f32 v59, v51, s0
	v_add_u32_e32 v60, 0x4000, v8
	ds_write_b16 v60, v52
	ds_write_b16 v60, v53 offset:132
	ds_write_b16 v60, v54 offset:264
	ds_write_b16 v60, v55 offset:396
	ds_write_b16 v60, v56 offset:528
	ds_write_b16 v60, v57 offset:660
	ds_write_b16 v60, v58 offset:792
	ds_write_b16 v60, v59 offset:924
	s_waitcnt vmcnt(3)
	v_cvt_pk_bf16_f32 v52, v64, s0
	v_cvt_pk_bf16_f32 v53, v65, s0
	v_cvt_pk_bf16_f32 v54, v66, s0
	v_cvt_pk_bf16_f32 v55, v67, s0
	s_waitcnt vmcnt(2)
	v_cvt_pk_bf16_f32 v56, v68, s0
	v_cvt_pk_bf16_f32 v57, v69, s0
	v_cvt_pk_bf16_f32 v58, v70, s0
	v_cvt_pk_bf16_f32 v59, v71, s0
	v_add_u32_e32 v60, 0x8000, v8
	ds_write_b16 v60, v52
	ds_write_b16 v60, v53 offset:132
	ds_write_b16 v60, v54 offset:264
	ds_write_b16 v60, v55 offset:396
	ds_write_b16 v60, v56 offset:528
	ds_write_b16 v60, v57 offset:660
	ds_write_b16 v60, v58 offset:792
	ds_write_b16 v60, v59 offset:924
	s_waitcnt vmcnt(1)
	v_cvt_pk_bf16_f32 v52, v72, s0
	v_cvt_pk_bf16_f32 v53, v73, s0
	v_cvt_pk_bf16_f32 v54, v74, s0
	v_cvt_pk_bf16_f32 v55, v75, s0
	s_waitcnt vmcnt(0)
	v_cvt_pk_bf16_f32 v56, v76, s0
	v_cvt_pk_bf16_f32 v57, v77, s0
	v_cvt_pk_bf16_f32 v58, v78, s0
	v_cvt_pk_bf16_f32 v59, v79, s0
	v_add_u32_e32 v60, 0xc000, v8
	ds_write_b16 v60, v52
	ds_write_b16 v60, v53 offset:132
	ds_write_b16 v60, v54 offset:264
	ds_write_b16 v60, v55 offset:396
	ds_write_b16 v60, v56 offset:528
	ds_write_b16 v60, v57 offset:660
	ds_write_b16 v60, v58 offset:792
	ds_write_b16 v60, v59 offset:924
	s_waitcnt lgkmcnt(0)
	s_barrier
	ds_read2_b32 v[14:15], v9 offset1:1
	ds_read2_b32 v[16:17], v9 offset0:2 offset1:3
	v_add_u32_e32 v61, 0x4000, v9
	ds_read2_b32 v[44:45], v61 offset1:1
	ds_read2_b32 v[46:47], v61 offset0:2 offset1:3
	v_add_u32_e32 v61, 0x8000, v9
	ds_read2_b32 v[64:65], v61 offset1:1
	ds_read2_b32 v[66:67], v61 offset0:2 offset1:3
	v_add_u32_e32 v61, 0xc000, v9
	ds_read2_b32 v[72:73], v61 offset1:1
	ds_read2_b32 v[74:75], v61 offset0:2 offset1:3
	v_addc_co_u32_e32 v7, vcc, 0, v7, vcc
	s_waitcnt lgkmcnt(0)
	global_store_dwordx4 v[6:7], v[14:17], off
	s_mov_b64 s[54:55], 0x20000
	v_lshl_add_u64 v[62:63], v[6:7], 0, s[54:55]
	global_store_dwordx4 v[62:63], v[44:47], off
	s_mov_b64 s[54:55], 0x40000
	v_lshl_add_u64 v[62:63], v[6:7], 0, s[54:55]
	global_store_dwordx4 v[62:63], v[64:67], off
	s_mov_b64 s[54:55], 0x60000
	v_lshl_add_u64 v[62:63], v[6:7], 0, s[54:55]
	global_store_dwordx4 v[62:63], v[72:75], off

; __device__ __forceinline__ u16 f2bf(float a) { return (u16)(pack2(a, 0.f) & 0xffffu); }
;     ...
;   {
;     int k = t >> 3, n0 = (t & 7) * 8;
;     const float4* s = (const float4*)(src + (size_t)(kt * 64 + k) * N + ntile * 64 + n0);
;     float4 a = s[0], b = s[1];
;     tl[(n0 + 0) * 66 + k] = f2bf(a.x); tl[(n0 + 1) * 66 + k] = f2bf(a.y);
;     tl[(n0 + 2) * 66 + k] = f2bf(a.z); tl[(n0 + 3) * 66 + k] = f2bf(a.w);
;     tl[(n0 + 4) * 66 + k] = f2bf(b.x); tl[(n0 + 5) * 66 + k] = f2bf(b.y);
;     tl[(n0 + 6) * 66 + k] = f2bf(b.z); tl[(n0 + 7) * 66 + k] = f2bf(b.w);
;   }
;   __syncthreads();
;   {
;     int n = t >> 3, kk0 = (t & 7) * 8;
;     int ng = ntile * 64 + n, np = ng;
;     if (mode == 1) {
;       if (ng >= 1792) { int j = ng - 1792; int hb = 0; if (j >= 1024) { j -= 1024; hb = 32; } np = 1792 + (j >> 5) * 64 + hb + (j & 31); }
;     } else if (mode == 2) {
;       int j = ng, hb = 0; if (j >= DFF) { j -= DFF; hb = 32; } np = (j >> 5) * 64 + hb + (j & 31);
;     }
;     const uint32_t* r = (const uint32_t*)(tl + n * 66 + kk0);
;     uint4 v = make_uint4(r[0], r[1], r[2], r[3]);
;     *(uint4*)(dst + (size_t)np * dld + kt * 64 + kk0) = v;
; __global__ void __launch_bounds__(NTHREADS, 2) fwd_megakernel(Params p_arg) {
;     ...
;       if (r < 960) { transpose_tile(pk->w_in + (size_t)l * 1024 * INW, wl + WOFF_IN, 1024, INW, r / 60, r % 60, 1, shm, tid); }
.LBB0_56:
	s_andn2_b64 vcc, exec, s[14:15]
	s_cbranch_vccnz .LBB0_37
	s_mov_b64 s[14:15], s[52:53]
	s_mul_hi_i32 s4, s12, 0xf00000
	s_mul_i32 s12, s12, 0xf00000
	s_mul_hi_i32 s13, s33, 0x88888889
	s_waitcnt lgkmcnt(0)
	s_add_u32 s14, s14, s12
	s_addc_u32 s15, s15, s4
	s_add_i32 s13, s13, s33
	s_lshr_b32 s4, s13, 31
	s_ashr_i32 s12, s13, 5
	s_add_i32 s4, s12, s4
	s_mul_i32 s12, s4, 60
	s_sub_i32 s13, s33, s12
	s_mov_b32 s58, 0x20000
	s_cmp_ge_u32 s13, 28
	s_cselect_b32 s58, 0x40000, s58
	s_lshl_b32 s12, s4, 6
	v_add_u32_e32 v5, s12, v1
	v_mov_b64_e32 v[6:7], s[14:15]
	v_mad_i64_i32 v[6:7], s[14:15], v5, s29, v[6:7]
	s_lshl_b32 s14, s13, 6
	s_ashr_i32 s15, s14, 31
	v_lshl_add_u64 v[6:7], s[14:15], 2, v[6:7]
	v_lshl_add_u64 v[6:7], v[6:7], 0, v[2:3]
	global_load_dwordx4 v[14:17], v[6:7], off
	global_load_dwordx4 v[18:21], v[6:7], off offset:16
	global_load_dwordx4 v[44:47], v[6:7], off offset:256
	global_load_dwordx4 v[48:51], v[6:7], off offset:272
	global_load_dwordx4 v[64:67], v[6:7], off offset:512
	global_load_dwordx4 v[68:71], v[6:7], off offset:528
	global_load_dwordx4 v[72:75], v[6:7], off offset:768
	global_load_dwordx4 v[76:79], v[6:7], off offset:784
	v_add_u32_e32 v6, s14, v1
	v_cmp_lt_i32_e32 vcc, s30, v6
	s_waitcnt vmcnt(7)
	v_cvt_pk_bf16_f32 v5, v14, s0
	v_cvt_pk_bf16_f32 v7, v15, s0
	v_cvt_pk_bf16_f32 v13, v16, s0
	v_cvt_pk_bf16_f32 v14, v17, s0
	s_waitcnt vmcnt(6)
	v_cvt_pk_bf16_f32 v15, v18, s0
	v_cvt_pk_bf16_f32 v16, v19, s0
	v_cvt_pk_bf16_f32 v17, v20, s0
	v_cvt_pk_bf16_f32 v18, v21, s0
	ds_write_b16 v8, v5
	ds_write_b16 v8, v7 offset:132
	ds_write_b16 v8, v13 offset:264
	ds_write_b16 v8, v14 offset:396
	ds_write_b16 v8, v15 offset:528
	ds_write_b16 v8, v16 offset:660
	ds_write_b16 v8, v17 offset:792
	ds_write_b16 v8, v18 offset:924
	s_waitcnt vmcnt(5)
	v_cvt_pk_bf16_f32 v52, v44, s0
	v_cvt_pk_bf16_f32 v53, v45, s0
	v_cvt_pk_bf16_f32 v54, v46, s0
	v_cvt_pk_bf16_f32 v55, v47, s0
	s_waitcnt vmcnt(4)
	v_cvt_pk_bf16_f32 v56, v48, s0
	v_cvt_pk_bf16_f32 v57, v49, s0
	v_cvt_pk_bf16_f32 v58, v50, s0
	v_cvt_pk_bf16_f32 v59, v51, s0
	v_add_u32_e32 v60, 0x4000, v8
	ds_write_b16 v60, v52
	ds_write_b16 v60, v53 offset:132
	ds_write_b16 v60, v54 offset:264
	ds_write_b16 v60, v55 offset:396
	ds_write_b16 v60, v56 offset:528
	ds_write_b16 v60, v57 offset:660
	ds_write_b16 v60, v58 offset:792
	ds_write_b16 v60, v59 offset:924
	s_waitcnt vmcnt(3)
	v_cvt_pk_bf16_f32 v52, v64, s0
	v_cvt_pk_bf16_f32 v53, v65, s0
	v_cvt_pk_bf16_f32 v54, v66, s0
	v_cvt_pk_bf16_f32 v55, v67, s0
	s_waitcnt vmcnt(2)
	v_cvt_pk_bf16_f32 v56, v68, s0
	v_cvt_pk_bf16_f32 v57, v69, s0
	v_cvt_pk_bf16_f32 v58, v70, s0
	v_cvt_pk_bf16_f32 v59, v71, s0
	v_add_u32_e32 v60, 0x8000, v8
	ds_write_b16 v60, v52
	ds_write_b16 v60, v53 offset:132
	ds_write_b16 v60, v54 offset:264
	ds_write_b16 v60, v55 offset:396
	ds_write_b16 v60, v56 offset:528
	ds_write_b16 v60, v57 offset:660
	ds_write_b16 v60, v58 offset:792
	ds_write_b16 v60, v59 offset:924
	s_waitcnt vmcnt(1)
	v_cvt_pk_bf16_f32 v52, v72, s0
	v_cvt_pk_bf16_f32 v53, v73, s0
	v_cvt_pk_bf16_f32 v54, v74, s0
	v_cvt_pk_bf16_f32 v55, v75, s0
	s_waitcnt vmcnt(0)
	v_cvt_pk_bf16_f32 v56, v76, s0
	v_cvt_pk_bf16_f32 v57, v77, s0
	v_cvt_pk_bf16_f32 v58, v78, s0
	v_cvt_pk_bf16_f32 v59, v79, s0
	v_add_u32_e32 v60, 0xc000, v8
	ds_write_b16 v60, v52
	ds_write_b16 v60, v53 offset:132
	ds_write_b16 v60, v54 offset:264
	ds_write_b16 v60, v55 offset:396
	ds_write_b16 v60, v56 offset:528
	ds_write_b16 v60, v57 offset:660
	ds_write_b16 v60, v58 offset:792
	ds_write_b16 v60, v59 offset:924
	s_waitcnt lgkmcnt(0)
	s_barrier
	s_and_saveexec_b64 s[14:15], vcc
	s_cbranch_execz .LBB0_36
	v_cmp_lt_u32_e32 vcc, s28, v6
	s_nop 1
	v_cndmask_b32_e32 v7, v11, v12, vcc
	v_add_lshl_u32 v6, v7, v6, 1
	v_cndmask_b32_e64 v5, 0, 32, vcc
	v_and_b32_e32 v6, 0x7fffffc0, v6
	v_or3_b32 v5, v6, v5, v10
	v_add_u32_e32 v6, 0x700, v5
	s_branch .LBB0_36
